# substitution-chain instructions per V-half MFMA = 2
# baseline (speedup 1.0000x reference)
.Lmy_ck_nz:
	s_mov_b32 s100, 0xe000
	s_cmp_eq_u32 s23, 0
	s_cselect_b32 s100, 0x1c000, s100
	s_mov_b32 s101, 0x12e00
	s_cselect_b32 s101, 0x22100, s101
	s_lshl_b32 s96, s23, 13
	s_add_i32 s97, s96, 0x18000
	s_add_i32 s96, s96, 0xa000
	v_add_u32_e32 v225, s100, v1
	v_add_u32_e32 v236, s100, v0
	v_add_u32_e32 v34, s100, v10
	v_add_u32_e32 v226, s100, v2
	v_add_u32_e32 v227, s100, v3
	v_add_u32_e32 v228, s100, v4
	v_add_u32_e32 v229, s100, v5
	v_add_u32_e32 v237, s100, v6
	v_add_u32_e32 v238, s100, v7
	v_add_u32_e32 v230, s96, v8
	v_add_u32_e32 v239, s96, v9
	v_add_u32_e32 v231, s97, v8
	v_add_u32_e32 v26, s101, v1
	v_add_u32_e32 v27, s101, v0
	v_add_u32_e32 v35, s101, v10
	v_add_u32_e32 v28, s101, v2
	v_add_u32_e32 v29, s101, v3
	v_add_u32_e32 v30, s101, v4
	v_add_u32_e32 v31, s101, v5
	v_add_u32_e32 v32, s101, v6
	v_add_u32_e32 v33, s101, v7
	ds_read_b64 v[80:81], v237
	ds_read_b64 v[82:83], v238
	ds_read_b32 v36, v239
	ds_read_b32 v37, v239 offset:256
	ds_read_b128 v[88:91], v225
	ds_read_b128 v[92:95], v225 offset:1024
	ds_read_b128 v[96:99], v225 offset:2048
	ds_read_b128 v[100:103], v225 offset:3072
	ds_read_b32 v104, v227 offset:4
	ds_read_b32 v105, v227 offset:76
	ds_read_b64 v[106:107], v227 offset:8
	ds_read_b64 v[108:109], v227 offset:40
	ds_read_b32 v126, v229 offset:4
	ds_read_b32 v127, v229 offset:76
	ds_read_b64 v[128:129], v229 offset:8
	ds_read_b64 v[130:131], v229 offset:40
	ds_read_b64 v[110:111], v228
	ds_read_b64 v[112:113], v228 offset:32
	ds_read_b64 v[114:115], v228 offset:64
	ds_read_b64 v[116:117], v228 offset:96
	ds_read_b64 v[118:119], v228 offset:8
	ds_read_b64 v[120:121], v228 offset:40
	ds_read_b64 v[122:123], v228 offset:72
	ds_read_b64 v[124:125], v228 offset:104
	s_waitcnt lgkmcnt(15)
	v_mfma_f32_16x16x4_f32 v[240:243], v80, v36, 0
	v_mfma_f32_16x16x4_f32 v[240:243], v81, v37, v[240:243]
	v_mfma_f32_16x16x4_f32 v[240:243], v88, v208, v[240:243]
	ds_read_b64 v[186:187], v34
	ds_read_b64 v[190:191], v34 offset:1024
	v_mfma_f32_16x16x4_f32 v[244:247], v89, v209, 0
	ds_read_b64 v[194:195], v34 offset:2048
	ds_read_b64 v[198:199], v34 offset:3072
	v_mfma_f32_16x16x4_f32 v[240:243], v90, v210, v[240:243]
	ds_read_b64 v[184:185], v236
	ds_read_b64 v[188:189], v236 offset:1024
	ds_read_b64 v[132:133], v237 offset:9984
	v_mfma_f32_16x16x4_f32 v[244:247], v91, v211, v[244:247]
	ds_read_b64 v[134:135], v238 offset:9984
	ds_read_b64 v[192:193], v236 offset:2048
	ds_read_b64 v[196:197], v236 offset:3072
	v_mfma_f32_16x16x4_f32 v[240:243], v92, v212, v[240:243]
	ds_read_b32 v38, v239 offset:2048
	ds_read_b32 v39, v239 offset:2304
	ds_read_b128 v[140:143], v225 offset:9984
	v_mfma_f32_16x16x4_f32 v[244:247], v93, v213, v[244:247]
	ds_read_b128 v[144:147], v225 offset:11008
	ds_read_b128 v[148:151], v225 offset:12032
	ds_read_b128 v[152:155], v225 offset:13056
	v_mfma_f32_16x16x4_f32 v[240:243], v94, v214, v[240:243]
	ds_read_b32 v156, v227 offset:9988
	ds_read_b32 v157, v227 offset:10060
	v_mfma_f32_16x16x4_f32 v[244:247], v95, v215, v[244:247]
	ds_read_b64 v[158:159], v227 offset:9992
	ds_read_b64 v[160:161], v227 offset:10024
	v_mfma_f32_16x16x4_f32 v[240:243], v96, v216, v[240:243]
	ds_read_b32 v178, v229 offset:9988
	ds_read_b32 v179, v229 offset:10060
	v_mfma_f32_16x16x4_f32 v[244:247], v97, v217, v[244:247]
	ds_read_b64 v[180:181], v229 offset:9992
	ds_read_b64 v[182:183], v229 offset:10024
	v_mfma_f32_16x16x4_f32 v[240:243], v98, v218, v[240:243]
	ds_read_b64 v[162:163], v228 offset:9984
	ds_read_b64 v[164:165], v228 offset:10016
	v_mfma_f32_16x16x4_f32 v[244:247], v99, v219, v[244:247]
	ds_read_b64 v[166:167], v228 offset:10048
	ds_read_b64 v[168:169], v228 offset:10080
	v_mfma_f32_16x16x4_f32 v[240:243], v100, v220, v[240:243]
	ds_read_b64 v[170:171], v228 offset:9992
	ds_read_b64 v[172:173], v228 offset:10024
	v_mfma_f32_16x16x4_f32 v[244:247], v101, v221, v[244:247]
	ds_read_b64 v[174:175], v228 offset:10056
	ds_read_b64 v[176:177], v228 offset:10088
	v_mfma_f32_16x16x4_f32 v[240:243], v102, v222, v[240:243]
	v_mfma_f32_16x16x4_f32 v[244:247], v103, v223, v[244:247]
	s_waitcnt lgkmcnt(15)
	v_mfma_f32_16x16x4_f32 v[208:211], v186, v36, v[208:211]
	s_nop 2
	v_pk_add_f32 v[240:241], v[240:241], v[244:245]
	v_pk_add_f32 v[242:243], v[242:243], v[246:247]
	v_mfma_f32_16x16x4_f32 v[212:215], v190, v36, v[212:215]
	v_fmac_f32_e32 v241, v104, v240
	v_pk_fma_f32 v[242:243], v[106:107], v[240:241], v[242:243] op_sel:[0,0,0] op_sel_hi:[1,0,1]
	v_mfma_f32_16x16x4_f32 v[216:219], v194, v36, v[216:219]
	v_pk_fma_f32 v[242:243], v[108:109], v[240:241], v[242:243] op_sel:[0,1,0] op_sel_hi:[1,1,1]
	v_fmac_f32_e32 v243, v105, v242
	v_mfma_f32_16x16x4_f32 v[72:75], v132, v38, 0
	ds_bpermute_b32 v204, v232, v240
	ds_bpermute_b32 v205, v232, v241
	v_mfma_f32_16x16x4_f32 v[72:75], v133, v39, v[72:75]
	ds_bpermute_b32 v206, v232, v242
	ds_bpermute_b32 v207, v232, v243
	v_mfma_f32_16x16x4_f32 v[220:223], v198, v36, v[220:223]
	s_waitcnt lgkmcnt(2)
	v_pk_fma_f32 v[240:241], v[110:111], v[204:205], v[240:241] op_sel:[0,0,0] op_sel_hi:[1,0,1]
	v_pk_fma_f32 v[240:241], v[112:113], v[204:205], v[240:241] op_sel:[0,1,0] op_sel_hi:[1,1,1]
	v_mfma_f32_16x16x4_f32 v[208:211], v187, v37, v[208:211]
	s_waitcnt lgkmcnt(0)
	v_pk_fma_f32 v[240:241], v[114:115], v[206:207], v[240:241] op_sel:[0,0,0] op_sel_hi:[1,0,1]
	v_pk_fma_f32 v[240:241], v[116:117], v[206:207], v[240:241] op_sel:[0,1,0] op_sel_hi:[1,1,1]
	v_mfma_f32_16x16x4_f32 v[212:215], v191, v37, v[212:215]
	v_pk_fma_f32 v[242:243], v[118:119], v[204:205], v[242:243] op_sel:[0,0,0] op_sel_hi:[1,0,1]
	v_pk_fma_f32 v[242:243], v[120:121], v[204:205], v[242:243] op_sel:[0,1,0] op_sel_hi:[1,1,1]
	v_mfma_f32_16x16x4_f32 v[216:219], v195, v37, v[216:219]
	v_pk_fma_f32 v[242:243], v[122:123], v[206:207], v[242:243] op_sel:[0,0,0] op_sel_hi:[1,0,1]
	v_pk_fma_f32 v[242:243], v[124:125], v[206:207], v[242:243] op_sel:[0,1,0] op_sel_hi:[1,1,1]
	v_mfma_f32_16x16x4_f32 v[220:223], v199, v37, v[220:223]
	v_fmac_f32_e32 v241, v126, v240
	v_pk_fma_f32 v[242:243], v[128:129], v[240:241], v[242:243] op_sel:[0,0,0] op_sel_hi:[1,0,1]
	v_pk_fma_f32 v[242:243], v[130:131], v[240:241], v[242:243] op_sel:[0,1,0] op_sel_hi:[1,1,1]
	v_fmac_f32_e32 v243, v127, v242
	v_mov_b32_e32 v252, v240
	v_mov_b32_e32 v253, v241
	v_mov_b32_e32 v254, v242
	v_mov_b32_e32 v255, v243
	s_nop 0
	v_permlane32_swap_b32_e32 v252, v254
	v_permlane32_swap_b32_e32 v253, v255
	s_nop 0
	v_mfma_f32_16x16x4_f32 v[208:211], v184, v252, v[208:211]
	ds_read_b128 v[88:91], v226
	v_mfma_f32_16x16x4_f32 v[212:215], v188, v252, v[212:215]
	ds_read_b128 v[92:95], v226 offset:64
	v_mfma_f32_16x16x4_f32 v[216:219], v192, v252, v[216:219]
	ds_read_b128 v[96:99], v226 offset:128
	v_mfma_f32_16x16x4_f32 v[220:223], v196, v252, v[220:223]
	ds_read_b128 v[100:103], v226 offset:192
	v_mfma_f32_16x16x4_f32 v[208:211], v185, v253, v[208:211]
	v_mfma_f32_16x16x4_f32 v[212:215], v189, v253, v[212:215]
	v_mfma_f32_16x16x4_f32 v[216:219], v193, v253, v[216:219]
	v_mfma_f32_16x16x4_f32 v[220:223], v197, v253, v[220:223]
	v_mfma_f32_16x16x4_f32 v[248:251], v82, v252, v[240:243]
	v_mfma_f32_16x16x4_f32 v[248:251], v83, v253, v[248:251]
	s_waitcnt lgkmcnt(3)
	v_pk_mul_f32 v[208:209], v[208:209], v[88:89]
	v_pk_mul_f32 v[210:211], v[210:211], v[90:91]
	s_nop 0
	v_mfma_f32_16x16x4_f32 v[72:75], v140, v208, v[72:75]
	s_waitcnt lgkmcnt(2)
	v_pk_mul_f32 v[212:213], v[212:213], v[92:93]
	v_mfma_f32_16x16x4_f32 v[244:247], v141, v209, 0
	v_pk_mul_f32 v[214:215], v[214:215], v[94:95]
	v_mfma_f32_16x16x4_f32 v[72:75], v142, v210, v[72:75]
	s_waitcnt lgkmcnt(1)
	v_pk_mul_f32 v[216:217], v[216:217], v[96:97]
	v_mfma_f32_16x16x4_f32 v[244:247], v143, v211, v[244:247]
	v_pk_mul_f32 v[218:219], v[218:219], v[98:99]
	v_mfma_f32_16x16x4_f32 v[72:75], v144, v212, v[72:75]
	s_waitcnt lgkmcnt(0)
	v_pk_mul_f32 v[220:221], v[220:221], v[100:101]
	v_mfma_f32_16x16x4_f32 v[244:247], v145, v213, v[244:247]
	v_pk_mul_f32 v[222:223], v[222:223], v[102:103]
	v_mfma_f32_16x16x4_f32 v[72:75], v146, v214, v[72:75]
	s_mov_b64 exec, s[98:99]
	ds_write_b32 v231, v248
	ds_write_b32 v231, v249 offset:256
	ds_write_b32 v231, v250 offset:512
	ds_write_b32 v231, v251 offset:768
	s_mov_b64 exec, -1
	ds_read_b64 v[186:187], v34 offset:9984
	ds_read_b64 v[190:191], v34 offset:11008
	v_mfma_f32_16x16x4_f32 v[244:247], v147, v215, v[244:247]
	ds_read_b64 v[194:195], v34 offset:12032
	ds_read_b64 v[198:199], v34 offset:13056
	v_mfma_f32_16x16x4_f32 v[72:75], v148, v216, v[72:75]
	ds_read_b64 v[184:185], v236 offset:9984
	ds_read_b64 v[188:189], v236 offset:11008
	ds_read_b64 v[80:81], v32
	v_mfma_f32_16x16x4_f32 v[244:247], v149, v217, v[244:247]
	ds_read_b64 v[82:83], v33
	ds_read_b32 v36, v239 offset:4096
	ds_read_b64 v[192:193], v236 offset:12032
	v_mfma_f32_16x16x4_f32 v[72:75], v150, v218, v[72:75]
	ds_read_b64 v[196:197], v236 offset:13056
	ds_read_b32 v37, v239 offset:4352
	ds_read_b128 v[88:91], v26
	v_mfma_f32_16x16x4_f32 v[244:247], v151, v219, v[244:247]
	ds_read_b128 v[92:95], v26 offset:1024
	ds_read_b128 v[96:99], v26 offset:2048
	ds_read_b128 v[100:103], v26 offset:3072
	v_mfma_f32_16x16x4_f32 v[72:75], v152, v220, v[72:75]
	ds_read_b32 v104, v29 offset:4
	ds_read_b32 v105, v29 offset:76
	ds_read_b64 v[106:107], v29 offset:8
	v_mfma_f32_16x16x4_f32 v[244:247], v153, v221, v[244:247]
	ds_read_b64 v[108:109], v29 offset:40
	ds_read_b32 v126, v31 offset:4
	ds_read_b32 v127, v31 offset:76
	v_mfma_f32_16x16x4_f32 v[72:75], v154, v222, v[72:75]
	ds_read_b64 v[128:129], v31 offset:8
	ds_read_b64 v[130:131], v31 offset:40
	ds_read_b64 v[110:111], v30
	v_mfma_f32_16x16x4_f32 v[244:247], v155, v223, v[244:247]
	ds_read_b64 v[112:113], v30 offset:32
	ds_read_b64 v[114:115], v30 offset:64
	ds_read_b64 v[116:117], v30 offset:96
	ds_read_b64 v[118:119], v30 offset:8
	ds_read_b64 v[120:121], v30 offset:40
	ds_read_b64 v[122:123], v30 offset:72
	ds_read_b64 v[124:125], v30 offset:104
	s_waitcnt lgkmcnt(15)
	v_mfma_f32_16x16x4_f32 v[208:211], v186, v38, v[208:211]
	s_nop 1
	v_pk_add_f32 v[72:73], v[72:73], v[244:245]
	v_pk_add_f32 v[74:75], v[74:75], v[246:247]
	v_mfma_f32_16x16x4_f32 v[212:215], v190, v38, v[212:215]
	v_fmac_f32_e32 v73, v156, v72
	v_pk_fma_f32 v[74:75], v[158:159], v[72:73], v[74:75] op_sel:[0,0,0] op_sel_hi:[1,0,1]
	v_mfma_f32_16x16x4_f32 v[216:219], v194, v38, v[216:219]
	v_pk_fma_f32 v[74:75], v[160:161], v[72:73], v[74:75] op_sel:[0,1,0] op_sel_hi:[1,1,1]
	v_fmac_f32_e32 v75, v157, v74
	v_mfma_f32_16x16x4_f32 v[240:243], v80, v36, 0
	ds_bpermute_b32 v204, v232, v72
	ds_bpermute_b32 v205, v232, v73
	v_mfma_f32_16x16x4_f32 v[240:243], v81, v37, v[240:243]
	ds_bpermute_b32 v206, v232, v74
	ds_bpermute_b32 v207, v232, v75
	v_mfma_f32_16x16x4_f32 v[220:223], v198, v38, v[220:223]
	s_waitcnt lgkmcnt(2)
	v_pk_fma_f32 v[72:73], v[162:163], v[204:205], v[72:73] op_sel:[0,0,0] op_sel_hi:[1,0,1]
	v_pk_fma_f32 v[72:73], v[164:165], v[204:205], v[72:73] op_sel:[0,1,0] op_sel_hi:[1,1,1]
	v_mfma_f32_16x16x4_f32 v[208:211], v187, v39, v[208:211]
	s_waitcnt lgkmcnt(0)
	v_pk_fma_f32 v[72:73], v[166:167], v[206:207], v[72:73] op_sel:[0,0,0] op_sel_hi:[1,0,1]
	v_pk_fma_f32 v[72:73], v[168:169], v[206:207], v[72:73] op_sel:[0,1,0] op_sel_hi:[1,1,1]
	v_mfma_f32_16x16x4_f32 v[212:215], v191, v39, v[212:215]
	v_pk_fma_f32 v[74:75], v[170:171], v[204:205], v[74:75] op_sel:[0,0,0] op_sel_hi:[1,0,1]
	v_pk_fma_f32 v[74:75], v[172:173], v[204:205], v[74:75] op_sel:[0,1,0] op_sel_hi:[1,1,1]
	v_mfma_f32_16x16x4_f32 v[216:219], v195, v39, v[216:219]
	v_pk_fma_f32 v[74:75], v[174:175], v[206:207], v[74:75] op_sel:[0,0,0] op_sel_hi:[1,0,1]
	v_pk_fma_f32 v[74:75], v[176:177], v[206:207], v[74:75] op_sel:[0,1,0] op_sel_hi:[1,1,1]
	v_mfma_f32_16x16x4_f32 v[220:223], v199, v39, v[220:223]
	v_fmac_f32_e32 v73, v178, v72
	v_pk_fma_f32 v[74:75], v[180:181], v[72:73], v[74:75] op_sel:[0,0,0] op_sel_hi:[1,0,1]
	v_pk_fma_f32 v[74:75], v[182:183], v[72:73], v[74:75] op_sel:[0,1,0] op_sel_hi:[1,1,1]
	v_fmac_f32_e32 v75, v179, v74
	v_mov_b32_e32 v252, v72
	v_mov_b32_e32 v253, v73
	v_mov_b32_e32 v254, v74
	v_mov_b32_e32 v255, v75
	s_nop 0
	v_permlane32_swap_b32_e32 v252, v254
	v_permlane32_swap_b32_e32 v253, v255
	s_nop 0
	v_mfma_f32_16x16x4_f32 v[208:211], v184, v252, v[208:211]
	ds_read_b128 v[140:143], v226 offset:9984
	v_mfma_f32_16x16x4_f32 v[212:215], v188, v252, v[212:215]
	ds_read_b128 v[144:147], v226 offset:10048
	v_mfma_f32_16x16x4_f32 v[216:219], v192, v252, v[216:219]
	ds_read_b128 v[148:151], v226 offset:10112
	v_mfma_f32_16x16x4_f32 v[220:223], v196, v252, v[220:223]
	ds_read_b128 v[152:155], v226 offset:10176
	v_mfma_f32_16x16x4_f32 v[208:211], v185, v253, v[208:211]
	v_mfma_f32_16x16x4_f32 v[212:215], v189, v253, v[212:215]
	v_mfma_f32_16x16x4_f32 v[216:219], v193, v253, v[216:219]
	v_mfma_f32_16x16x4_f32 v[220:223], v197, v253, v[220:223]
	v_mfma_f32_16x16x4_f32 v[248:251], v134, v252, v[72:75]
	v_mfma_f32_16x16x4_f32 v[248:251], v135, v253, v[248:251]
	s_waitcnt lgkmcnt(3)
	v_pk_mul_f32 v[208:209], v[208:209], v[140:141]
	v_pk_mul_f32 v[210:211], v[210:211], v[142:143]
	s_nop 0
	v_mfma_f32_16x16x4_f32 v[240:243], v88, v208, v[240:243]
	s_waitcnt lgkmcnt(2)
	v_pk_mul_f32 v[212:213], v[212:213], v[144:145]
	v_mfma_f32_16x16x4_f32 v[244:247], v89, v209, 0
	v_pk_mul_f32 v[214:215], v[214:215], v[146:147]
	v_mfma_f32_16x16x4_f32 v[240:243], v90, v210, v[240:243]
	s_waitcnt lgkmcnt(1)
	v_pk_mul_f32 v[216:217], v[216:217], v[148:149]
	v_mfma_f32_16x16x4_f32 v[244:247], v91, v211, v[244:247]
	v_pk_mul_f32 v[218:219], v[218:219], v[150:151]
	v_mfma_f32_16x16x4_f32 v[240:243], v92, v212, v[240:243]
	s_waitcnt lgkmcnt(0)
	v_pk_mul_f32 v[220:221], v[220:221], v[152:153]
	v_mfma_f32_16x16x4_f32 v[244:247], v93, v213, v[244:247]
	v_pk_mul_f32 v[222:223], v[222:223], v[154:155]
	v_mfma_f32_16x16x4_f32 v[240:243], v94, v214, v[240:243]
	s_mov_b64 exec, s[98:99]
	ds_write_b32 v231, v248 offset:2048
	ds_write_b32 v231, v249 offset:2304
	ds_write_b32 v231, v250 offset:2560
	ds_write_b32 v231, v251 offset:2816
	s_mov_b64 exec, -1
	ds_read_b64 v[186:187], v35
	ds_read_b64 v[190:191], v35 offset:1024
	v_mfma_f32_16x16x4_f32 v[244:247], v95, v215, v[244:247]
	ds_read_b64 v[194:195], v35 offset:2048
	ds_read_b64 v[198:199], v35 offset:3072
	v_mfma_f32_16x16x4_f32 v[240:243], v96, v216, v[240:243]
	ds_read_b64 v[184:185], v27
	ds_read_b64 v[188:189], v27 offset:1024
	ds_read_b64 v[132:133], v32 offset:9984
	v_mfma_f32_16x16x4_f32 v[244:247], v97, v217, v[244:247]
	ds_read_b64 v[134:135], v33 offset:9984
	ds_read_b32 v38, v239 offset:6144
	ds_read_b64 v[192:193], v27 offset:2048
	v_mfma_f32_16x16x4_f32 v[240:243], v98, v218, v[240:243]
	ds_read_b64 v[196:197], v27 offset:3072
	ds_read_b32 v39, v239 offset:6400
	ds_read_b128 v[140:143], v26 offset:9984
	v_mfma_f32_16x16x4_f32 v[244:247], v99, v219, v[244:247]
	ds_read_b128 v[144:147], v26 offset:11008
	ds_read_b128 v[148:151], v26 offset:12032
	ds_read_b128 v[152:155], v26 offset:13056
	v_mfma_f32_16x16x4_f32 v[240:243], v100, v220, v[240:243]
	ds_read_b32 v156, v29 offset:9988
	ds_read_b32 v157, v29 offset:10060
	ds_read_b64 v[158:159], v29 offset:9992
	v_mfma_f32_16x16x4_f32 v[244:247], v101, v221, v[244:247]
	ds_read_b64 v[160:161], v29 offset:10024
	ds_read_b32 v178, v31 offset:9988
	ds_read_b32 v179, v31 offset:10060
	v_mfma_f32_16x16x4_f32 v[240:243], v102, v222, v[240:243]
	ds_read_b64 v[180:181], v31 offset:9992
	ds_read_b64 v[182:183], v31 offset:10024
	ds_read_b64 v[162:163], v30 offset:9984
	v_mfma_f32_16x16x4_f32 v[244:247], v103, v223, v[244:247]
	ds_read_b64 v[164:165], v30 offset:10016
	ds_read_b64 v[166:167], v30 offset:10048
	ds_read_b64 v[168:169], v30 offset:10080
	ds_read_b64 v[170:171], v30 offset:9992
	ds_read_b64 v[172:173], v30 offset:10024
	ds_read_b64 v[174:175], v30 offset:10056
	ds_read_b64 v[176:177], v30 offset:10088
	s_waitcnt lgkmcnt(15)
	v_mfma_f32_16x16x4_f32 v[208:211], v186, v36, v[208:211]
	s_nop 1
	v_pk_add_f32 v[240:241], v[240:241], v[244:245]
	v_pk_add_f32 v[242:243], v[242:243], v[246:247]
	v_mfma_f32_16x16x4_f32 v[212:215], v190, v36, v[212:215]
	v_fmac_f32_e32 v241, v104, v240
	v_pk_fma_f32 v[242:243], v[106:107], v[240:241], v[242:243] op_sel:[0,0,0] op_sel_hi:[1,0,1]
	v_mfma_f32_16x16x4_f32 v[216:219], v194, v36, v[216:219]
	v_pk_fma_f32 v[242:243], v[108:109], v[240:241], v[242:243] op_sel:[0,1,0] op_sel_hi:[1,1,1]
	v_fmac_f32_e32 v243, v105, v242
	v_mfma_f32_16x16x4_f32 v[72:75], v132, v38, 0
	ds_bpermute_b32 v204, v232, v240
	ds_bpermute_b32 v205, v232, v241
	v_mfma_f32_16x16x4_f32 v[72:75], v133, v39, v[72:75]
	ds_bpermute_b32 v206, v232, v242
	ds_bpermute_b32 v207, v232, v243
	v_mfma_f32_16x16x4_f32 v[220:223], v198, v36, v[220:223]
	s_waitcnt lgkmcnt(2)
	v_pk_fma_f32 v[240:241], v[110:111], v[204:205], v[240:241] op_sel:[0,0,0] op_sel_hi:[1,0,1]
	v_pk_fma_f32 v[240:241], v[112:113], v[204:205], v[240:241] op_sel:[0,1,0] op_sel_hi:[1,1,1]
	v_mfma_f32_16x16x4_f32 v[208:211], v187, v37, v[208:211]
	s_waitcnt lgkmcnt(0)
	v_pk_fma_f32 v[240:241], v[114:115], v[206:207], v[240:241] op_sel:[0,0,0] op_sel_hi:[1,0,1]
	v_pk_fma_f32 v[240:241], v[116:117], v[206:207], v[240:241] op_sel:[0,1,0] op_sel_hi:[1,1,1]
	v_mfma_f32_16x16x4_f32 v[212:215], v191, v37, v[212:215]
	v_pk_fma_f32 v[242:243], v[118:119], v[204:205], v[242:243] op_sel:[0,0,0] op_sel_hi:[1,0,1]
	v_pk_fma_f32 v[242:243], v[120:121], v[204:205], v[242:243] op_sel:[0,1,0] op_sel_hi:[1,1,1]
	v_mfma_f32_16x16x4_f32 v[216:219], v195, v37, v[216:219]
	v_pk_fma_f32 v[242:243], v[122:123], v[206:207], v[242:243] op_sel:[0,0,0] op_sel_hi:[1,0,1]
	v_pk_fma_f32 v[242:243], v[124:125], v[206:207], v[242:243] op_sel:[0,1,0] op_sel_hi:[1,1,1]
	v_mfma_f32_16x16x4_f32 v[220:223], v199, v37, v[220:223]
	v_fmac_f32_e32 v241, v126, v240
	v_pk_fma_f32 v[242:243], v[128:129], v[240:241], v[242:243] op_sel:[0,0,0] op_sel_hi:[1,0,1]
	v_pk_fma_f32 v[242:243], v[130:131], v[240:241], v[242:243] op_sel:[0,1,0] op_sel_hi:[1,1,1]
	v_fmac_f32_e32 v243, v127, v242
	v_mov_b32_e32 v252, v240
	v_mov_b32_e32 v253, v241
	v_mov_b32_e32 v254, v242
	v_mov_b32_e32 v255, v243
	s_nop 0
	v_permlane32_swap_b32_e32 v252, v254
	v_permlane32_swap_b32_e32 v253, v255
	s_nop 0
	v_mfma_f32_16x16x4_f32 v[208:211], v184, v252, v[208:211]
	ds_read_b128 v[88:91], v28
	v_mfma_f32_16x16x4_f32 v[212:215], v188, v252, v[212:215]
	ds_read_b128 v[92:95], v28 offset:64
	v_mfma_f32_16x16x4_f32 v[216:219], v192, v252, v[216:219]
	ds_read_b128 v[96:99], v28 offset:128
	v_mfma_f32_16x16x4_f32 v[220:223], v196, v252, v[220:223]
	ds_read_b128 v[100:103], v28 offset:192
	v_mfma_f32_16x16x4_f32 v[208:211], v185, v253, v[208:211]
	v_mfma_f32_16x16x4_f32 v[212:215], v189, v253, v[212:215]
	v_mfma_f32_16x16x4_f32 v[216:219], v193, v253, v[216:219]
	v_mfma_f32_16x16x4_f32 v[220:223], v197, v253, v[220:223]
	v_mfma_f32_16x16x4_f32 v[248:251], v82, v252, v[240:243]
	v_mfma_f32_16x16x4_f32 v[248:251], v83, v253, v[248:251]
	s_waitcnt lgkmcnt(3)
	v_pk_mul_f32 v[208:209], v[208:209], v[88:89]
	v_pk_mul_f32 v[210:211], v[210:211], v[90:91]
	s_nop 0
	v_mfma_f32_16x16x4_f32 v[72:75], v140, v208, v[72:75]
	s_waitcnt lgkmcnt(2)
	v_pk_mul_f32 v[212:213], v[212:213], v[92:93]
	v_mfma_f32_16x16x4_f32 v[244:247], v141, v209, 0
	v_pk_mul_f32 v[214:215], v[214:215], v[94:95]
	v_mfma_f32_16x16x4_f32 v[72:75], v142, v210, v[72:75]
	s_waitcnt lgkmcnt(1)
	v_pk_mul_f32 v[216:217], v[216:217], v[96:97]
	v_mfma_f32_16x16x4_f32 v[244:247], v143, v211, v[244:247]
	v_pk_mul_f32 v[218:219], v[218:219], v[98:99]
	v_mfma_f32_16x16x4_f32 v[72:75], v144, v212, v[72:75]
	s_waitcnt lgkmcnt(0)
	v_pk_mul_f32 v[220:221], v[220:221], v[100:101]
	v_mfma_f32_16x16x4_f32 v[244:247], v145, v213, v[244:247]
	v_pk_mul_f32 v[222:223], v[222:223], v[102:103]
	v_mfma_f32_16x16x4_f32 v[72:75], v146, v214, v[72:75]
	s_mov_b64 exec, s[98:99]
	ds_write_b32 v231, v248 offset:4096
	ds_write_b32 v231, v249 offset:4352
	ds_write_b32 v231, v250 offset:4608
	ds_write_b32 v231, v251 offset:4864
	s_mov_b64 exec, -1
	ds_read_b64 v[186:187], v35 offset:9984
	ds_read_b64 v[190:191], v35 offset:11008
	v_mfma_f32_16x16x4_f32 v[244:247], v147, v215, v[244:247]
	ds_read_b64 v[194:195], v35 offset:12032
	ds_read_b64 v[198:199], v35 offset:13056
	v_mfma_f32_16x16x4_f32 v[72:75], v148, v216, v[72:75]
	ds_read_b64 v[184:185], v27 offset:9984
	ds_read_b64 v[188:189], v27 offset:11008
	v_mfma_f32_16x16x4_f32 v[244:247], v149, v217, v[244:247]
	ds_read_b64 v[192:193], v27 offset:12032
	ds_read_b64 v[196:197], v27 offset:13056
	v_mfma_f32_16x16x4_f32 v[72:75], v150, v218, v[72:75]
	v_mfma_f32_16x16x4_f32 v[244:247], v151, v219, v[244:247]
	v_mfma_f32_16x16x4_f32 v[72:75], v152, v220, v[72:75]
	v_mfma_f32_16x16x4_f32 v[244:247], v153, v221, v[244:247]
	v_mfma_f32_16x16x4_f32 v[72:75], v154, v222, v[72:75]
	v_mfma_f32_16x16x4_f32 v[244:247], v155, v223, v[244:247]
	s_waitcnt lgkmcnt(7)
	v_mfma_f32_16x16x4_f32 v[208:211], v186, v38, v[208:211]
	s_nop 2
	v_pk_add_f32 v[72:73], v[72:73], v[244:245]
	v_pk_add_f32 v[74:75], v[74:75], v[246:247]
	s_waitcnt lgkmcnt(6)
	v_mfma_f32_16x16x4_f32 v[212:215], v190, v38, v[212:215]
	v_fmac_f32_e32 v73, v156, v72
	v_pk_fma_f32 v[74:75], v[158:159], v[72:73], v[74:75] op_sel:[0,0,0] op_sel_hi:[1,0,1]
	s_waitcnt lgkmcnt(5)
	v_mfma_f32_16x16x4_f32 v[216:219], v194, v38, v[216:219]
	v_pk_fma_f32 v[74:75], v[160:161], v[72:73], v[74:75] op_sel:[0,1,0] op_sel_hi:[1,1,1]
	v_fmac_f32_e32 v75, v157, v74
	s_waitcnt lgkmcnt(4)
	v_mfma_f32_16x16x4_f32 v[220:223], v198, v38, v[220:223]
	ds_bpermute_b32 v204, v232, v72
	ds_bpermute_b32 v205, v232, v73
	v_mfma_f32_16x16x4_f32 v[208:211], v187, v39, v[208:211]
	ds_bpermute_b32 v206, v232, v74
	ds_bpermute_b32 v207, v232, v75
	v_mfma_f32_16x16x4_f32 v[212:215], v191, v39, v[212:215]
	s_waitcnt lgkmcnt(2)
	v_pk_fma_f32 v[72:73], v[162:163], v[204:205], v[72:73] op_sel:[0,0,0] op_sel_hi:[1,0,1]
	v_pk_fma_f32 v[72:73], v[164:165], v[204:205], v[72:73] op_sel:[0,1,0] op_sel_hi:[1,1,1]
	v_mfma_f32_16x16x4_f32 v[216:219], v195, v39, v[216:219]
	s_waitcnt lgkmcnt(0)
	v_pk_fma_f32 v[72:73], v[166:167], v[206:207], v[72:73] op_sel:[0,0,0] op_sel_hi:[1,0,1]
	v_pk_fma_f32 v[72:73], v[168:169], v[206:207], v[72:73] op_sel:[0,1,0] op_sel_hi:[1,1,1]
	v_mfma_f32_16x16x4_f32 v[220:223], v199, v39, v[220:223]
	v_pk_fma_f32 v[74:75], v[170:171], v[204:205], v[74:75] op_sel:[0,0,0] op_sel_hi:[1,0,1]
	v_pk_fma_f32 v[74:75], v[172:173], v[204:205], v[74:75] op_sel:[0,1,0] op_sel_hi:[1,1,1]
	v_pk_fma_f32 v[74:75], v[174:175], v[206:207], v[74:75] op_sel:[0,0,0] op_sel_hi:[1,0,1]
	v_pk_fma_f32 v[74:75], v[176:177], v[206:207], v[74:75] op_sel:[0,1,0] op_sel_hi:[1,1,1]
	v_fmac_f32_e32 v73, v178, v72
	v_pk_fma_f32 v[74:75], v[180:181], v[72:73], v[74:75] op_sel:[0,0,0] op_sel_hi:[1,0,1]
	v_pk_fma_f32 v[74:75], v[182:183], v[72:73], v[74:75] op_sel:[0,1,0] op_sel_hi:[1,1,1]
	v_fmac_f32_e32 v75, v179, v74
	v_mov_b32_e32 v252, v72
	v_mov_b32_e32 v253, v73
	v_mov_b32_e32 v254, v74
	v_mov_b32_e32 v255, v75
	s_nop 0
	v_permlane32_swap_b32_e32 v252, v254
	v_permlane32_swap_b32_e32 v253, v255
	s_nop 0
	v_mfma_f32_16x16x4_f32 v[208:211], v184, v252, v[208:211]
	ds_read_b128 v[140:143], v28 offset:9984
	v_mfma_f32_16x16x4_f32 v[212:215], v188, v252, v[212:215]
	ds_read_b128 v[144:147], v28 offset:10048
	v_mfma_f32_16x16x4_f32 v[216:219], v192, v252, v[216:219]
	ds_read_b128 v[148:151], v28 offset:10112
	v_mfma_f32_16x16x4_f32 v[220:223], v196, v252, v[220:223]
	ds_read_b128 v[152:155], v28 offset:10176
	v_mfma_f32_16x16x4_f32 v[208:211], v185, v253, v[208:211]
	v_mfma_f32_16x16x4_f32 v[212:215], v189, v253, v[212:215]
	v_mfma_f32_16x16x4_f32 v[216:219], v193, v253, v[216:219]
	v_mfma_f32_16x16x4_f32 v[220:223], v197, v253, v[220:223]
	v_mfma_f32_16x16x4_f32 v[248:251], v134, v252, v[72:75]
	v_mfma_f32_16x16x4_f32 v[248:251], v135, v253, v[248:251]
	s_waitcnt lgkmcnt(3)
	v_pk_mul_f32 v[208:209], v[208:209], v[140:141]
	v_pk_mul_f32 v[210:211], v[210:211], v[142:143]
	s_waitcnt lgkmcnt(2)
	v_pk_mul_f32 v[212:213], v[212:213], v[144:145]
	v_pk_mul_f32 v[214:215], v[214:215], v[146:147]
	s_waitcnt lgkmcnt(1)
	v_pk_mul_f32 v[216:217], v[216:217], v[148:149]
	v_pk_mul_f32 v[218:219], v[218:219], v[150:151]
	s_waitcnt lgkmcnt(0)
	v_pk_mul_f32 v[220:221], v[220:221], v[152:153]
	v_pk_mul_f32 v[222:223], v[222:223], v[154:155]
	s_mov_b64 exec, s[98:99]
	s_nop 0
	ds_write_b32 v231, v248 offset:6144
	ds_write_b32 v231, v249 offset:6400
	ds_write_b32 v231, v250 offset:6656
	ds_write_b32 v231, v251 offset:6912
	s_mov_b64 exec, -1
	s_branch .LBB0_655
